# phase-1 GEMM load balance: the 64 workgroups that own an extra indexer tile hand their fourth gates-GEMM tile to 64 workgroups on the same XCD (only when the grid is 256)
# speedup vs baseline: 1.0012x; 1.0001x over previous
;     __host__ __device__ bool next(int i, Unit& u) const {
;         const long L = (long)i * G + c; if (L >= nwg) return false;
;         int wgid = (int)L; { const int q = nwg / NXCD, r = nwg % NXCD, xcd = wgid % NXCD, off = wgid / NXCD; wgid = (xcd < r ? xcd * (q + 1) : r * (q + 1) + (xcd - r) * q) + off; }
; template <class Epi, class Sched, bool ALIGN_EPI = false, bool SP2 = false, bool F8 = false>
; __device__ __forceinline__ void gemm_phase(PG8_LAS unsigned char* lds, const Gemm g, const Sched& S, const Epi& E) {
;     ...
;         const bool has_next = S.next(ui + 1, nxt);
.LBB0_1115:
	s_add_i32 s59, s59, 1
	v_readlane_b32 s19, v251, 27
	s_mul_i32 s19, s59, s19
	s_mul_hi_u32 s23, s59, s94
	s_add_i32 s23, s23, s19
	s_mul_i32 s19, s59, s94
	s_add_u32 s44, s19, s97
	s_addc_u32 s45, s23, s95
	s_sub_u32 s19, s97, 0x80
	s_mov_b32 s23, 0x7fffffff
	s_cmp_lt_u32 s19, 64
	s_cselect_b32 s19, 0x300, s23
	s_cmp_lg_u32 s94, 0x100
	s_cselect_b32 s19, s23, s19
	s_cmp_ge_u32 s44, s19
	s_cselect_b32 s44, 0x1000, s44
	s_sub_u32 s19, s44, 0x400
	s_cmp_lt_u32 s19, 64
	s_cselect_b32 s19, 0x80, 0
	s_cmp_lg_u32 s94, 0x100
	s_cselect_b32 s19, 0, s19
	s_sub_u32 s44, s44, s19
	v_cmp_gt_i64_e32 vcc, s[44:45], v[180:181]
	v_cmp_lt_i64_e64 s[38:39], s[44:45], v[178:179]
	s_cbranch_vccnz .LBB0_1121
	s_ashr_i32 s19, s44, 31
	s_lshr_b32 s19, s19, 29
	s_add_i32 s19, s44, s19
	s_and_b32 s23, s19, -8
	s_sub_i32 s23, s44, s23
	s_cmp_gt_i32 s23, -1
	s_mov_b64 s[34:35], -1
	s_cbranch_scc0 .LBB0_1118
	s_lshl_b32 s28, s23, 7
	s_mov_b64 s[34:35], 0
